# in-projection epilogue fast path for the raw-u units of sequence tails: only the one row group that holds stored rows is processed
# speedup vs baseline: 1.0071x; 1.0047x over previous
.LBB0_1093:
	s_and_b64 vcc, exec, s[2:3]
	s_cbranch_vccz .LBB0_1422
	s_cmp_lt_u32 s35, 2
	s_cbranch_scc1 .Lfi_entry
	s_cmp_eq_u32 s35, 4
	s_cbranch_scc1 .Lfi_k4
.Lfi_k4_slow:
	v_readlane_b32 s2, v252, 42
	s_add_i32 s71, s71, s2
	v_add_u32_e32 v0, s71, v209
	ds_read_b128 v[150:153], v0 offset:4096
	ds_read_b128 v[146:149], v0 offset:4112
	ds_read_b128 v[142:145], v0 offset:4224
	ds_read_b128 v[138:141], v0 offset:4240
	ds_read_b128 v[0:3], v181
	s_cmp_eq_u32 s35, 2
	s_cselect_b32 s26, s85, s66
	s_cselect_b32 s27, s84, s65
	s_cselect_b32 s49, s49, s74
	s_waitcnt lgkmcnt(0)
	v_mov_b32_e32 v4, v1
	v_mov_b32_e32 v5, v2
	v_mov_b32_e32 v1, v3
	v_pk_add_f32 v[0:1], v[4:5], v[0:1]
	s_cselect_b32 s33, s37, s33
	v_add_f32_e32 v0, v0, v1
	v_fmamk_f32 v0, v0, 0x3a800000, v212
	v_mul_f32_e32 v1, 0x4b800000, v0
	v_cmp_gt_f32_e32 vcc, s59, v0
	s_lshl_b32 s36, s36, 8
	s_add_i32 s16, s36, s20
	v_cndmask_b32_e32 v0, v0, v1, vcc
	v_rsq_f32_e32 v0, v0
	s_add_i32 s2, s16, 0xffff0000
	s_lshr_b32 s90, s2, 5
	s_ashr_i32 s18, s16, 11
	s_lshl_b64 s[2:3], s[90:91], 17
	s_add_u32 s2, s27, s2
	v_or_b32_e32 v1, s16, v163
	v_mul_f32_e32 v2, 0x45800000, v0
	s_addc_u32 s3, s26, s3
	v_mov_b32_e32 v185, v97
	v_cndmask_b32_e32 v186, v0, v2, vcc
	v_cmp_gt_i32_e64 s[10:11], s72, v1
	v_lshl_add_u64 v[0:1], s[2:3], 0, v[184:185]
	s_mov_b64 s[2:3], 0x18000
	s_ashr_i32 s19, s18, 31
	v_bitop3_b32 v2, s16, v217, v163 bitop3:0xc8
	v_lshl_add_u64 v[188:189], v[0:1], 0, s[2:3]
	s_lshl_b64 s[2:3], s[18:19], 17
	v_add_u32_e32 v96, 0xfffff880, v2
	s_add_u32 s2, s33, s2
	s_addc_u32 s3, s49, s3
	v_lshlrev_b64 v[0:1], 10, v[96:97]
	v_cmp_lt_u32_e64 s[12:13], s86, v2
	v_lshl_add_u64 v[190:191], s[2:3], 0, v[0:1]
	v_pk_fma_f32 v[136:137], v[136:137], v[186:187], v[152:153] op_sel_hi:[1,0,1]
	v_pk_fma_f32 v[134:135], v[134:135], v[186:187], v[150:151] op_sel_hi:[1,0,1]
	v_pk_fma_f32 v[132:133], v[132:133], v[186:187], v[148:149] op_sel_hi:[1,0,1]
	v_pk_fma_f32 v[130:131], v[130:131], v[186:187], v[146:147] op_sel_hi:[1,0,1]
	s_cmp_lt_i32 s35, 1
	s_mov_b64 s[14:15], -1
	s_cbranch_scc1 .LBB0_1104
	v_mov_b64_e32 v[4:5], v[130:131]
	v_mov_b64_e32 v[0:1], v[134:135]
	s_cmp_gt_i32 s35, 3
	v_mov_b64_e32 v[6:7], v[132:133]
	v_mov_b64_e32 v[2:3], v[136:137]
	s_cbranch_scc1 .LBB0_1103
	s_cmp_lg_u32 s35, 1
	s_cbranch_scc0 .LBB0_1100
	v_lshlrev_b64 v[0:1], 2, v[182:183]
	v_lshl_add_u64 v[2:3], v[188:189], 0, v[0:1]
	v_lshl_add_u64 v[0:1], v[190:191], 0, v[0:1]
	v_cndmask_b32_e64 v0, 0, v0, s[12:13]
	v_cndmask_b32_e64 v1, 0, v1, s[12:13]
	v_cndmask_b32_e64 v1, v3, v1, s[10:11]
	v_cndmask_b32_e64 v0, v2, v0, s[10:11]
	v_cmp_ne_u64_e32 vcc, 0, v[0:1]
	s_and_saveexec_b64 s[14:15], vcc
	s_cbranch_execz .LBB0_1099
	global_store_dwordx4 v[0:1], v[134:137], off
	global_store_dwordx4 v[0:1], v[130:133], off offset:16

.Lfi_k4:
	s_and_b32 s10, s36, 7
	s_cmp_eq_u32 s10, 7
	s_cbranch_scc0 .Lfi_k4_slow
	s_cmp_eq_u32 s20, 0
	s_cbranch_scc1 .LBB0_1422
	v_readlane_b32 s10, v252, 42
	v_add_u32_e32 v1, s71, v208
	s_add_i32 s10, s10, s71
	v_add_u32_e32 v0, s10, v209
	ds_read_b128 v[186:189], v1 offset:2816
	ds_read_b128 v[150:153], v0 offset:4096
	ds_read_b128 v[146:149], v0 offset:4112
	ds_read_b128 v[142:145], v0 offset:4224
	ds_read_b128 v[138:141], v0 offset:4240
	s_lshr_b32 s10, s36, 3
	s_mul_i32 s10, s10, 0xf000
	s_add_u32 s12, s44, s10
	s_addc_u32 s13, s45, 0
	v_add_u32_e32 v2, -1, v163
	v_lshlrev_b32_e32 v2, 12, v2
	v_lshl_add_u32 v2, v182, 2, v2
	s_waitcnt lgkmcnt(0)
	v_add_f32_e32 v4, v186, v187
	v_add_f32_e32 v5, v188, v189
	v_add_f32_e32 v4, v4, v5
	v_fmamk_f32 v4, v4, 0x3a800000, v212
	v_rsq_f32_e32 v6, v4
	v_cmp_lt_u32_e32 vcc, 0, v163
	s_nop 0
	v_pk_fma_f32 v[22:23], v[22:23], v[6:7], v[152:153] op_sel_hi:[1,0,1]
	v_pk_fma_f32 v[20:21], v[20:21], v[6:7], v[150:151] op_sel_hi:[1,0,1]
	v_pk_fma_f32 v[18:19], v[18:19], v[6:7], v[148:149] op_sel_hi:[1,0,1]
	v_pk_fma_f32 v[16:17], v[16:17], v[6:7], v[146:147] op_sel_hi:[1,0,1]
	v_pk_fma_f32 v[14:15], v[14:15], v[6:7], v[144:145] op_sel_hi:[1,0,1]
	v_pk_fma_f32 v[12:13], v[12:13], v[6:7], v[142:143] op_sel_hi:[1,0,1]
	v_pk_fma_f32 v[10:11], v[10:11], v[6:7], v[140:141] op_sel_hi:[1,0,1]
	v_pk_fma_f32 v[8:9], v[8:9], v[6:7], v[138:139] op_sel_hi:[1,0,1]
	s_and_saveexec_b64 s[10:11], vcc
	global_store_dwordx4 v2, v[20:23], s[12:13]
	global_store_dwordx4 v2, v[16:19], s[12:13] offset:16
	global_store_dwordx4 v2, v[12:15], s[12:13] offset:128
	global_store_dwordx4 v2, v[8:11], s[12:13] offset:144
	s_or_b64 exec, exec, s[10:11]
	s_branch .LBB0_1422
